# g21 + longest-first (LPT) ordering of dynamically fetched P3/P5 items (heavy query tiles first, tiny ones last)
# speedup vs baseline: 1.0065x; 1.0065x over previous
; DI void mla_item(const Params& p, int it, unsigned char* smem, u16* mb_out) {
;     ...
;   const int k = it >> 9, r = it & 511, cls = r >> 8, bh = r & 255, b = bh >> 3, hp = bh & 7;
;   const int pi = k >> 1, qt = (k & 1) ? (2 * pi + cls) : (15 - 2 * pi - cls);
;   const int q0 = qt * 128;
; DI void phase3(const Params& p, int bid, int nblk, unsigned char* smem, u16* mb_out) {
;     ...
;   for (int it = bid; it < 4096; it += nblk) { mla_item(p, it, smem, mb_out); __syncthreads(); }
.Ldyn3_skip_b:
	s_barrier
	ds_read_b32 v136, v139
	s_waitcnt lgkmcnt(0)
	v_readfirstlane_b32 s98, v136
	s_add_i32 s98, s98, s92
	s_lshr_b32 s99, s98, 9
	s_lshl_b32 s100, s99, 1
	s_sub_i32 s101, 15, s100
	s_cmp_lt_u32 s99, 4
	s_cselect_b32 s100, s100, s101
	s_lshl_b32 s100, s100, 9
	s_and_b32 s71, s98, 0x1ff
	s_or_b32 s71, s71, s100
	s_lshl_b32 s70, s71, 8
	s_cmpk_lt_i32 s98, 0x1000
	v_readlane_b32 s1, v245, 24
	s_cbranch_scc0 .LBB0_463

; DI void selwin_item(const Params& p, int it, unsigned char* smem, u16* y_out) {
;     ...
;   const int k = it >> 9, r = it & 511, cls = r >> 7, bg = r & 127, b = bg >> 2, g = bg & 3;
;   const int pi = k >> 1, lo_ = pi * 4 + cls, qt = (k & 1) ? lo_ : (63 - lo_);
;   const int s0 = qt * 32, cur = s0 >> 6, h = g * 4 + wave;
; DI void phase5(const Params& p, int bid, int nblk, unsigned char* smem, u16* y_out) {
;   for (int it = bid; it < 8192; it += nblk) selwin_item(p, it, smem, y_out);
.Ldyn5_skip_b:
	s_barrier
	ds_read_b32 v184, v187
	s_waitcnt lgkmcnt(0)
	v_readfirstlane_b32 s98, v184
	s_add_i32 s98, s98, s92
	s_lshr_b32 s99, s98, 9
	s_lshl_b32 s100, s99, 1
	s_sub_i32 s101, 31, s100
	s_cmp_lt_u32 s99, 8
	s_cselect_b32 s100, s100, s101
	s_lshl_b32 s100, s100, 9
	s_and_b32 s58, s98, 0x1ff
	s_or_b32 s58, s58, s100
	s_cmpk_lt_i32 s98, 0x2000
	s_cbranch_scc0 .LBB0_754
